# baseline (speedup 1.0000x reference)
; __device__ __forceinline__ void df_unit_p128(ATT_LAS unsigned char* lds, const bf16_t* Q, const bf16_t* __restrict__ K, const bf16_t* __restrict__ V, bf16_t* O, int b, int h, int qb,
;                                              float lam, float post, const float* __restrict__ sub_g, const int wv) {
;     ...
;     const int kxb = r32 * 256 + (((mp * 8 + hi) ^ (r32 & 15)) * 16);
;     const int vread = D8_V0 + ((lane >> 4) & 1) * 32 + (lane & 3) * 8 + (4 * hi + ((lane & 15) >> 2)) * 64;
.LBB0_220:
	s_mov_b32 m0, s35
	s_waitcnt vmcnt(0) lgkmcnt(0)
	s_barrier
	ds_read_b128 v[66:69], v248 offset:32768
	ds_read_b128 v[70:73], v249 offset:32768
	ds_read_b128 v[74:77], v250 offset:32768
	ds_read_b128 v[78:81], v251 offset:32768
	s_add_u32 s98, s16, s42
	s_addc_u32 s99, s17, s43
	global_load_lds_dwordx4 v226, s[98:99]
	s_waitcnt lgkmcnt(3)
	v_mfma_f32_32x32x16_bf16 v[114:129], v[66:69], v[154:157], 0
	ds_read_b128 v[66:69], v248 offset:40960
	s_waitcnt lgkmcnt(3)
	v_mfma_f32_32x32x16_bf16 v[114:129], v[70:73], v[150:153], v[114:129]
	ds_read_b128 v[70:73], v249 offset:40960
	s_mov_b32 m0, s36
	s_nop 0
	global_load_lds_dwordx4 v224, s[98:99]
	s_waitcnt lgkmcnt(3)
	v_mfma_f32_32x32x16_bf16 v[114:129], v[74:77], v[146:149], v[114:129]
	ds_read_b128 v[74:77], v250 offset:40960
	s_waitcnt lgkmcnt(3)
	v_mfma_f32_32x32x16_bf16 v[114:129], v[78:81], v[142:145], v[114:129]
	ds_read_b128 v[78:81], v251 offset:40960
	s_mov_b32 m0, s37
	s_nop 0
	global_load_lds_dwordx4 v222, s[98:99]
	s_waitcnt lgkmcnt(3)
	v_mfma_f32_32x32x16_bf16 v[98:113], v[66:69], v[154:157], 0
	ds_read_b128 v[66:69], v248 offset:49152
	s_waitcnt lgkmcnt(3)
	v_mfma_f32_32x32x16_bf16 v[98:113], v[70:73], v[150:153], v[98:113]
	ds_read_b128 v[70:73], v249 offset:49152
	s_mov_b32 m0, s38
	s_nop 0
	global_load_lds_dwordx4 v220, s[98:99]
	s_waitcnt lgkmcnt(3)
	v_mfma_f32_32x32x16_bf16 v[98:113], v[74:77], v[146:149], v[98:113]
	ds_read_b128 v[74:77], v250 offset:49152
	s_waitcnt lgkmcnt(3)
	v_mfma_f32_32x32x16_bf16 v[98:113], v[78:81], v[142:145], v[98:113]
	v_exp_f32_e32 v114, v114
	v_exp_f32_e32 v115, v115
	v_exp_f32_e32 v116, v116
	v_exp_f32_e32 v117, v117
	ds_read_b128 v[78:81], v251 offset:49152
	s_mov_b32 m0, s19
	s_add_u32 s98, s16, 0x12440000
	s_addc_u32 s99, s17, 0
	global_load_lds_dwordx4 v228, s[98:99]
	s_waitcnt lgkmcnt(3)
	v_mfma_f32_32x32x16_bf16 v[82:97], v[66:69], v[154:157], 0
	v_add_f32_e32 v210, v114, v115
	v_add_f32_e32 v211, v117, v116
	v_cvt_pk_bf16_f32 v130, v114, v115
	v_cvt_pk_bf16_f32 v131, v116, v117
	ds_read_b128 v[194:197], v248 offset:57344
	s_waitcnt lgkmcnt(3)
	v_mfma_f32_32x32x16_bf16 v[82:97], v[70:73], v[150:153], v[82:97]
	v_exp_f32_e32 v118, v118
	v_exp_f32_e32 v119, v119
	v_exp_f32_e32 v120, v120
	v_exp_f32_e32 v121, v121
	ds_read_b128 v[198:201], v249 offset:57344
	s_add_i32 m0, s7, 0x8400
	s_add_u32 s98, s16, 0x12448000
	s_addc_u32 s99, s17, 0
	global_load_lds_dwordx4 v228, s[98:99]
	s_waitcnt lgkmcnt(3)
	v_mfma_f32_32x32x16_bf16 v[82:97], v[74:77], v[146:149], v[82:97]
	v_add_f32_e32 v212, v118, v119
	v_add_f32_e32 v210, v212, v210
	v_add_f32_e32 v213, v121, v120
	v_add_f32_e32 v211, v213, v211
	v_cvt_pk_bf16_f32 v132, v118, v119
	v_cvt_pk_bf16_f32 v133, v120, v121
	ds_read_b128 v[202:205], v250 offset:57344
	s_waitcnt lgkmcnt(3)
	v_mfma_f32_32x32x16_bf16 v[82:97], v[78:81], v[142:145], v[82:97]
	v_exp_f32_e32 v122, v122
	v_exp_f32_e32 v123, v123
	v_exp_f32_e32 v124, v124
	v_exp_f32_e32 v125, v125
	ds_read_b128 v[206:209], v251 offset:57344
	s_add_i32 m0, s7, 0x8800
	s_add_u32 s98, s16, 0x12450000
	s_addc_u32 s99, s17, 0
	global_load_lds_dwordx4 v228, s[98:99]
	s_waitcnt lgkmcnt(3)
	v_mfma_f32_32x32x16_bf16 v[66:81], v[194:197], v[154:157], 0
	v_add_f32_e32 v212, v122, v123
	v_add_f32_e32 v210, v212, v210
	v_add_f32_e32 v213, v125, v124
	v_add_f32_e32 v211, v213, v211
	v_cvt_pk_bf16_f32 v134, v122, v123
	v_cvt_pk_bf16_f32 v135, v124, v125
	s_waitcnt lgkmcnt(2)
	v_mfma_f32_32x32x16_bf16 v[66:81], v[198:201], v[150:153], v[66:81]
	v_exp_f32_e32 v126, v126
	v_exp_f32_e32 v127, v127
	v_exp_f32_e32 v128, v128
	v_exp_f32_e32 v129, v129
	s_add_i32 m0, s7, 0x8c00
	s_add_u32 s98, s16, 0x12458000
	s_addc_u32 s99, s17, 0
	s_mov_b32 s18, s39
	global_load_lds_dwordx4 v228, s[98:99]
	ds_read_b64_tr_b16 v[214:215], v252
	ds_read_b64_tr_b16 v[216:217], v252 offset:512
	s_waitcnt lgkmcnt(3)
	v_mfma_f32_32x32x16_bf16 v[66:81], v[202:205], v[146:149], v[66:81]
	v_add_f32_e32 v212, v126, v127
	v_add_f32_e32 v210, v212, v210
	v_add_f32_e32 v213, v129, v128
	v_add_f32_e32 v211, v213, v211
	v_cvt_pk_bf16_f32 v136, v126, v127
	v_cvt_pk_bf16_f32 v137, v128, v129
	ds_read_b64_tr_b16 v[114:115], v252 offset:1024
	ds_read_b64_tr_b16 v[116:117], v252 offset:1536
	s_waitcnt lgkmcnt(4)
	v_mfma_f32_32x32x16_bf16 v[66:81], v[206:209], v[142:145], v[66:81]
	v_exp_f32_e32 v98, v98
	v_exp_f32_e32 v99, v99
	v_exp_f32_e32 v100, v100
	v_exp_f32_e32 v101, v101
	s_waitcnt lgkmcnt(2)
	v_mfma_f32_32x32x16_bf16 v[2:17], v[214:217], v[158:161], v[2:17]
	ds_read_b64_tr_b16 v[118:119], v252 offset:2048
	ds_read_b64_tr_b16 v[120:121], v252 offset:2560
	v_add_f32_e32 v212, v98, v99
	v_add_f32_e32 v210, v212, v210
	v_add_f32_e32 v213, v101, v100
	v_add_f32_e32 v211, v213, v211
	v_cvt_pk_bf16_f32 v138, v98, v99
	v_cvt_pk_bf16_f32 v139, v100, v101
	s_waitcnt lgkmcnt(2)
	v_mfma_f32_32x32x16_bf16 v[2:17], v[114:117], v[162:165], v[2:17]
	ds_read_b64_tr_b16 v[214:215], v252 offset:3072
	ds_read_b64_tr_b16 v[216:217], v252 offset:3584
	s_waitcnt lgkmcnt(2)
	v_mfma_f32_32x32x16_bf16 v[2:17], v[118:121], v[166:169], v[2:17]
	ds_read_b64_tr_b16 v[114:115], v252 offset:4096
	ds_read_b64_tr_b16 v[116:117], v252 offset:4608
	v_exp_f32_e32 v102, v102
	v_exp_f32_e32 v103, v103
	v_exp_f32_e32 v104, v104
	v_exp_f32_e32 v105, v105
	s_waitcnt lgkmcnt(2)
	v_mfma_f32_32x32x16_bf16 v[2:17], v[214:217], v[170:173], v[2:17]
	ds_read_b64_tr_b16 v[118:119], v252 offset:5120
	ds_read_b64_tr_b16 v[120:121], v252 offset:5632
	v_add_f32_e32 v212, v102, v103
	v_add_f32_e32 v210, v212, v210
	v_add_f32_e32 v213, v105, v104
	v_add_f32_e32 v211, v213, v211
	v_cvt_pk_bf16_f32 v140, v102, v103
	v_cvt_pk_bf16_f32 v141, v104, v105
	s_waitcnt lgkmcnt(2)
	v_mfma_f32_32x32x16_bf16 v[2:17], v[114:117], v[174:177], v[2:17]
	ds_read_b64_tr_b16 v[214:215], v252 offset:6144
	ds_read_b64_tr_b16 v[216:217], v252 offset:6656
	s_waitcnt lgkmcnt(2)
	v_mfma_f32_32x32x16_bf16 v[2:17], v[118:121], v[178:181], v[2:17]
	ds_read_b64_tr_b16 v[114:115], v252 offset:7168
	ds_read_b64_tr_b16 v[116:117], v252 offset:7680
	v_exp_f32_e32 v106, v106
	v_exp_f32_e32 v107, v107
	v_exp_f32_e32 v108, v108
	v_exp_f32_e32 v109, v109
	s_waitcnt lgkmcnt(2)
	v_mfma_f32_32x32x16_bf16 v[2:17], v[214:217], v[182:185], v[2:17]
	ds_read_b64_tr_b16 v[118:119], v252 offset:8192
	ds_read_b64_tr_b16 v[120:121], v252 offset:8704
	v_add_f32_e32 v212, v106, v107
	v_add_f32_e32 v210, v212, v210
	v_add_f32_e32 v213, v109, v108
	v_add_f32_e32 v211, v213, v211
	v_cvt_pk_bf16_f32 v190, v106, v107
	v_cvt_pk_bf16_f32 v191, v108, v109
	s_waitcnt lgkmcnt(2)
	v_mfma_f32_32x32x16_bf16 v[2:17], v[114:117], v[186:189], v[2:17]
	ds_read_b64_tr_b16 v[214:215], v252 offset:9216
	ds_read_b64_tr_b16 v[216:217], v252 offset:9728
	v_exp_f32_e32 v110, v110
	v_exp_f32_e32 v111, v111
	v_exp_f32_e32 v112, v112
	v_exp_f32_e32 v113, v113
	s_waitcnt lgkmcnt(2)
	v_mfma_f32_32x32x16_bf16 v[50:65], v[118:121], v[158:161], v[50:65]
	ds_read_b64_tr_b16 v[114:115], v252 offset:10240
	ds_read_b64_tr_b16 v[116:117], v252 offset:10752
	s_waitcnt lgkmcnt(2)
	v_mfma_f32_32x32x16_bf16 v[50:65], v[214:217], v[162:165], v[50:65]
	ds_read_b64_tr_b16 v[118:119], v252 offset:11264
	ds_read_b64_tr_b16 v[120:121], v252 offset:11776
	v_add_f32_e32 v212, v110, v111
	v_add_f32_e32 v210, v212, v210
	v_add_f32_e32 v213, v113, v112
	v_add_f32_e32 v211, v213, v211
	v_cvt_pk_bf16_f32 v192, v110, v111
	v_cvt_pk_bf16_f32 v193, v112, v113
	s_waitcnt lgkmcnt(2)
	v_mfma_f32_32x32x16_bf16 v[50:65], v[114:117], v[166:169], v[50:65]
	ds_read_b64_tr_b16 v[214:215], v252 offset:12288
	ds_read_b64_tr_b16 v[216:217], v252 offset:12800
	v_exp_f32_e32 v82, v82
	v_exp_f32_e32 v83, v83
	v_exp_f32_e32 v84, v84
	v_exp_f32_e32 v85, v85
	s_waitcnt lgkmcnt(2)
	v_mfma_f32_32x32x16_bf16 v[50:65], v[118:121], v[170:173], v[50:65]
	ds_read_b64_tr_b16 v[114:115], v252 offset:13312
	ds_read_b64_tr_b16 v[116:117], v252 offset:13824
	s_waitcnt lgkmcnt(2)
	v_mfma_f32_32x32x16_bf16 v[50:65], v[214:217], v[174:177], v[50:65]
	ds_read_b64_tr_b16 v[118:119], v252 offset:14336
	ds_read_b64_tr_b16 v[120:121], v252 offset:14848
	v_add_f32_e32 v212, v82, v83
	v_add_f32_e32 v210, v212, v210
	v_add_f32_e32 v213, v85, v84
	v_add_f32_e32 v211, v213, v211
	v_cvt_pk_bf16_f32 v194, v82, v83
	v_cvt_pk_bf16_f32 v195, v84, v85
	s_waitcnt lgkmcnt(2)
	v_mfma_f32_32x32x16_bf16 v[50:65], v[114:117], v[178:181], v[50:65]
	ds_read_b64_tr_b16 v[214:215], v252 offset:15360
	ds_read_b64_tr_b16 v[216:217], v252 offset:15872
	v_exp_f32_e32 v86, v86
	v_exp_f32_e32 v87, v87
	v_exp_f32_e32 v88, v88
	v_exp_f32_e32 v89, v89
	s_waitcnt lgkmcnt(2)
	v_mfma_f32_32x32x16_bf16 v[50:65], v[118:121], v[182:185], v[50:65]
	ds_read_b64_tr_b16 v[114:115], v252 offset:16384
	ds_read_b64_tr_b16 v[116:117], v252 offset:16896
	v_add_f32_e32 v212, v86, v87
	v_add_f32_e32 v210, v212, v210
	v_add_f32_e32 v213, v89, v88
	v_add_f32_e32 v211, v213, v211
	v_cvt_pk_bf16_f32 v196, v86, v87
	v_cvt_pk_bf16_f32 v197, v88, v89
	s_waitcnt lgkmcnt(2)
	v_mfma_f32_32x32x16_bf16 v[50:65], v[214:217], v[186:189], v[50:65]
	ds_read_b64_tr_b16 v[118:119], v252 offset:17408
	ds_read_b64_tr_b16 v[120:121], v252 offset:17920
	s_waitcnt lgkmcnt(2)
	v_mfma_f32_32x32x16_bf16 v[34:49], v[114:117], v[158:161], v[34:49]
	ds_read_b64_tr_b16 v[214:215], v252 offset:18432
	ds_read_b64_tr_b16 v[216:217], v252 offset:18944
	v_exp_f32_e32 v90, v90
	v_exp_f32_e32 v91, v91
	v_exp_f32_e32 v92, v92
	v_exp_f32_e32 v93, v93
	s_waitcnt lgkmcnt(2)
	v_mfma_f32_32x32x16_bf16 v[34:49], v[118:121], v[162:165], v[34:49]
	ds_read_b64_tr_b16 v[114:115], v252 offset:19456
	ds_read_b64_tr_b16 v[116:117], v252 offset:19968
	v_add_f32_e32 v212, v90, v91
	v_add_f32_e32 v210, v212, v210
	v_add_f32_e32 v213, v93, v92
	v_add_f32_e32 v211, v213, v211
	v_cvt_pk_bf16_f32 v198, v90, v91
	v_cvt_pk_bf16_f32 v199, v92, v93
	s_waitcnt lgkmcnt(2)
	v_mfma_f32_32x32x16_bf16 v[34:49], v[214:217], v[166:169], v[34:49]
	ds_read_b64_tr_b16 v[118:119], v252 offset:20480
	ds_read_b64_tr_b16 v[120:121], v252 offset:20992
	v_exp_f32_e32 v94, v94
	v_exp_f32_e32 v95, v95
	v_exp_f32_e32 v96, v96
	v_exp_f32_e32 v97, v97
	s_waitcnt lgkmcnt(2)
	v_mfma_f32_32x32x16_bf16 v[34:49], v[114:117], v[170:173], v[34:49]
	ds_read_b64_tr_b16 v[214:215], v252 offset:21504
	ds_read_b64_tr_b16 v[216:217], v252 offset:22016
	s_waitcnt lgkmcnt(2)
	v_mfma_f32_32x32x16_bf16 v[34:49], v[118:121], v[174:177], v[34:49]
	ds_read_b64_tr_b16 v[114:115], v252 offset:22528
	ds_read_b64_tr_b16 v[116:117], v252 offset:23040
	v_add_f32_e32 v212, v94, v95
	v_add_f32_e32 v210, v212, v210
	v_add_f32_e32 v213, v97, v96
	v_add_f32_e32 v211, v213, v211
	v_cvt_pk_bf16_f32 v200, v94, v95
	v_cvt_pk_bf16_f32 v201, v96, v97
	s_waitcnt lgkmcnt(2)
	v_mfma_f32_32x32x16_bf16 v[34:49], v[214:217], v[178:181], v[34:49]
	ds_read_b64_tr_b16 v[118:119], v252 offset:23552
	ds_read_b64_tr_b16 v[120:121], v252 offset:24064
	v_exp_f32_e32 v66, v66
	v_exp_f32_e32 v67, v67
	v_exp_f32_e32 v68, v68
	v_exp_f32_e32 v69, v69
	s_waitcnt lgkmcnt(2)
	v_mfma_f32_32x32x16_bf16 v[34:49], v[114:117], v[182:185], v[34:49]
	ds_read_b64_tr_b16 v[214:215], v252 offset:24576
	ds_read_b64_tr_b16 v[216:217], v252 offset:25088
	s_waitcnt lgkmcnt(2)
; __device__ __forceinline__ void df_unit_p128(ATT_LAS unsigned char* lds, const bf16_t* Q, const bf16_t* __restrict__ K, const bf16_t* __restrict__ V, bf16_t* O, int b, int h, int qb,
;                                              float lam, float post, const float* __restrict__ sub_g, const int wv) {
;     ...
;     const int kxb = r32 * 256 + (((mp * 8 + hi) ^ (r32 & 15)) * 16);
;     const int vread = D8_V0 + ((lane >> 4) & 1) * 32 + (lane & 3) * 8 + (4 * hi + ((lane & 15) >> 2)) * 64;
	v_mfma_f32_32x32x16_bf16 v[34:49], v[118:121], v[186:189], v[34:49]
	ds_read_b64_tr_b16 v[114:115], v252 offset:25600
	ds_read_b64_tr_b16 v[116:117], v252 offset:26112
	v_add_f32_e32 v212, v66, v67
	v_add_f32_e32 v210, v212, v210
	v_add_f32_e32 v213, v69, v68
	v_add_f32_e32 v211, v213, v211
	v_cvt_pk_bf16_f32 v202, v66, v67
	v_cvt_pk_bf16_f32 v203, v68, v69
	s_waitcnt lgkmcnt(2)
	v_mfma_f32_32x32x16_bf16 v[18:33], v[214:217], v[158:161], v[18:33]
	ds_read_b64_tr_b16 v[118:119], v252 offset:26624
	ds_read_b64_tr_b16 v[120:121], v252 offset:27136
	v_exp_f32_e32 v70, v70
	v_exp_f32_e32 v71, v71
	v_exp_f32_e32 v72, v72
	v_exp_f32_e32 v73, v73
	s_waitcnt lgkmcnt(2)
	v_mfma_f32_32x32x16_bf16 v[18:33], v[114:117], v[162:165], v[18:33]
	ds_read_b64_tr_b16 v[214:215], v252 offset:27648
	ds_read_b64_tr_b16 v[216:217], v252 offset:28160
	v_add_f32_e32 v212, v70, v71
	v_add_f32_e32 v210, v212, v210
	v_add_f32_e32 v213, v73, v72
	v_add_f32_e32 v211, v213, v211
	v_cvt_pk_bf16_f32 v204, v70, v71
	v_cvt_pk_bf16_f32 v205, v72, v73
	s_waitcnt lgkmcnt(2)
	v_mfma_f32_32x32x16_bf16 v[18:33], v[118:121], v[166:169], v[18:33]
	ds_read_b64_tr_b16 v[114:115], v252 offset:28672
	ds_read_b64_tr_b16 v[116:117], v252 offset:29184
	s_waitcnt lgkmcnt(2)
	v_mfma_f32_32x32x16_bf16 v[18:33], v[214:217], v[170:173], v[18:33]
	ds_read_b64_tr_b16 v[118:119], v252 offset:29696
	ds_read_b64_tr_b16 v[120:121], v252 offset:30208
	v_exp_f32_e32 v74, v74
	v_exp_f32_e32 v75, v75
	v_exp_f32_e32 v76, v76
	v_exp_f32_e32 v77, v77
	s_waitcnt lgkmcnt(2)
	v_mfma_f32_32x32x16_bf16 v[18:33], v[114:117], v[174:177], v[18:33]
	ds_read_b64_tr_b16 v[214:215], v252 offset:30720
	ds_read_b64_tr_b16 v[216:217], v252 offset:31232
	v_add_f32_e32 v212, v74, v75
	v_add_f32_e32 v210, v212, v210
	v_add_f32_e32 v213, v77, v76
	v_add_f32_e32 v211, v213, v211
	v_cvt_pk_bf16_f32 v206, v74, v75
	v_cvt_pk_bf16_f32 v207, v76, v77
	s_waitcnt lgkmcnt(2)
	v_mfma_f32_32x32x16_bf16 v[18:33], v[118:121], v[178:181], v[18:33]
	ds_read_b64_tr_b16 v[114:115], v252 offset:31744
	ds_read_b64_tr_b16 v[116:117], v252 offset:32256
	s_waitcnt lgkmcnt(2)
	v_mfma_f32_32x32x16_bf16 v[18:33], v[214:217], v[182:185], v[18:33]
	v_exp_f32_e32 v78, v78
	v_exp_f32_e32 v79, v79
	v_exp_f32_e32 v80, v80
	v_exp_f32_e32 v81, v81
	s_waitcnt lgkmcnt(0)
	v_mfma_f32_32x32x16_bf16 v[18:33], v[114:117], v[186:189], v[18:33]
	v_add_f32_e32 v212, v78, v79
	v_add_f32_e32 v210, v212, v210
	v_add_f32_e32 v213, v81, v80
	v_add_f32_e32 v211, v213, v211
	v_cvt_pk_bf16_f32 v208, v78, v79
	v_cvt_pk_bf16_f32 v209, v80, v81
	v_add_f32_e32 v241, v211, v210
	s_waitcnt vmcnt(0) lgkmcnt(0)
	s_barrier
	ds_read_b128 v[66:69], v248
	ds_read_b128 v[70:73], v249
	ds_read_b128 v[74:77], v250
	ds_read_b128 v[78:81], v251
	s_mov_b32 m0, s33
	s_add_u32 s98, s16, s44
	s_addc_u32 s99, s17, s45
	global_load_lds_dwordx4 v226, s[98:99]
	s_waitcnt lgkmcnt(3)
	v_mfma_f32_32x32x16_bf16 v[114:129], v[66:69], v[154:157], 0
	ds_read_b128 v[66:69], v248 offset:8192
	s_waitcnt lgkmcnt(3)
	v_mfma_f32_32x32x16_bf16 v[114:129], v[70:73], v[150:153], v[114:129]
	ds_read_b128 v[70:73], v249 offset:8192
	s_add_i32 m0, s35, 0x8400
	s_nop 0
	global_load_lds_dwordx4 v224, s[98:99]
	s_waitcnt lgkmcnt(3)
	v_mfma_f32_32x32x16_bf16 v[114:129], v[74:77], v[146:149], v[114:129]
	ds_read_b128 v[74:77], v250 offset:8192
	s_waitcnt lgkmcnt(3)
	v_mfma_f32_32x32x16_bf16 v[114:129], v[78:81], v[142:145], v[114:129]
	ds_read_b128 v[78:81], v251 offset:8192
	s_add_i32 m0, s35, 0x8800
	s_nop 0
	global_load_lds_dwordx4 v222, s[98:99]
	s_waitcnt lgkmcnt(3)
	v_mfma_f32_32x32x16_bf16 v[98:113], v[66:69], v[154:157], 0
	ds_read_b128 v[66:69], v248 offset:16384
	s_waitcnt lgkmcnt(3)
	v_mfma_f32_32x32x16_bf16 v[98:113], v[70:73], v[150:153], v[98:113]
	ds_read_b128 v[70:73], v249 offset:16384
	s_add_i32 m0, s35, 0x8c00
	s_nop 0
	global_load_lds_dwordx4 v220, s[98:99]
	s_waitcnt lgkmcnt(3)
	v_mfma_f32_32x32x16_bf16 v[98:113], v[74:77], v[146:149], v[98:113]
	ds_read_b128 v[74:77], v250 offset:16384
	s_waitcnt lgkmcnt(3)
	v_mfma_f32_32x32x16_bf16 v[98:113], v[78:81], v[142:145], v[98:113]
	v_exp_f32_e32 v114, v114
	v_exp_f32_e32 v115, v115
	v_exp_f32_e32 v116, v116
	v_exp_f32_e32 v117, v117
	ds_read_b128 v[78:81], v251 offset:16384
	s_mov_b32 m0, s7
	s_add_u32 s98, s16, 0x12480000
	s_addc_u32 s99, s17, 0
	global_load_lds_dwordx4 v228, s[98:99]
	s_waitcnt lgkmcnt(3)
	v_mfma_f32_32x32x16_bf16 v[82:97], v[66:69], v[154:157], 0
	v_add_f32_e32 v210, v114, v115
	v_add_f32_e32 v211, v117, v116
	v_cvt_pk_bf16_f32 v158, v114, v115
	v_cvt_pk_bf16_f32 v159, v116, v117
	ds_read_b128 v[174:177], v248 offset:24576
	s_waitcnt lgkmcnt(3)
	v_mfma_f32_32x32x16_bf16 v[82:97], v[70:73], v[150:153], v[82:97]
	v_exp_f32_e32 v118, v118
	v_exp_f32_e32 v119, v119
	v_exp_f32_e32 v120, v120
	v_exp_f32_e32 v121, v121
	ds_read_b128 v[178:181], v249 offset:24576
	s_mov_b32 m0, s30
	s_add_u32 s98, s16, 0x12488000
	s_addc_u32 s99, s17, 0
	global_load_lds_dwordx4 v228, s[98:99]
	s_waitcnt lgkmcnt(3)
	v_mfma_f32_32x32x16_bf16 v[82:97], v[74:77], v[146:149], v[82:97]
	v_add_f32_e32 v212, v118, v119
	v_add_f32_e32 v210, v212, v210
	v_add_f32_e32 v213, v121, v120
	v_add_f32_e32 v211, v213, v211
	v_cvt_pk_bf16_f32 v160, v118, v119
	v_cvt_pk_bf16_f32 v161, v120, v121
	ds_read_b128 v[182:185], v250 offset:24576
	s_waitcnt lgkmcnt(3)
	v_mfma_f32_32x32x16_bf16 v[82:97], v[78:81], v[142:145], v[82:97]
	v_exp_f32_e32 v122, v122
	v_exp_f32_e32 v123, v123
	v_exp_f32_e32 v124, v124
	v_exp_f32_e32 v125, v125
	ds_read_b128 v[186:189], v251 offset:24576
	s_mov_b32 m0, s31
	s_add_u32 s98, s16, 0x12490000
	s_addc_u32 s99, s17, 0
	global_load_lds_dwordx4 v228, s[98:99]
	s_waitcnt lgkmcnt(3)
; __device__ __forceinline__ void df_unit_p128(ATT_LAS unsigned char* lds, const bf16_t* Q, const bf16_t* __restrict__ K, const bf16_t* __restrict__ V, bf16_t* O, int b, int h, int qb,
;                                              float lam, float post, const float* __restrict__ sub_g, const int wv) {
;     ...
;     const int kxb = r32 * 256 + (((mp * 8 + hi) ^ (r32 & 15)) * 16);
;     const int vread = D8_V0 + ((lane >> 4) & 1) * 32 + (lane & 3) * 8 + (4 * hi + ((lane & 15) >> 2)) * 64;
	v_mfma_f32_32x32x16_bf16 v[66:81], v[174:177], v[154:157], 0
	v_add_f32_e32 v212, v122, v123
	v_add_f32_e32 v210, v212, v210
	v_add_f32_e32 v213, v125, v124
	v_add_f32_e32 v211, v213, v211
	v_cvt_pk_bf16_f32 v162, v122, v123
	v_cvt_pk_bf16_f32 v163, v124, v125
	s_waitcnt lgkmcnt(2)
	v_mfma_f32_32x32x16_bf16 v[66:81], v[178:181], v[150:153], v[66:81]
	v_exp_f32_e32 v126, v126
	v_exp_f32_e32 v127, v127
	v_exp_f32_e32 v128, v128
	v_exp_f32_e32 v129, v129
	s_mov_b32 m0, s34
	s_add_u32 s98, s16, 0x12498000
	s_addc_u32 s99, s17, 0
	global_load_lds_dwordx4 v228, s[98:99]
	ds_read_b64_tr_b16 v[214:215], v253
	ds_read_b64_tr_b16 v[216:217], v253 offset:512
	s_waitcnt lgkmcnt(3)
	v_mfma_f32_32x32x16_bf16 v[66:81], v[182:185], v[146:149], v[66:81]
	v_add_f32_e32 v212, v126, v127
	v_add_f32_e32 v210, v212, v210
	v_add_f32_e32 v213, v129, v128
	v_add_f32_e32 v211, v213, v211
	v_cvt_pk_bf16_f32 v164, v126, v127
	v_cvt_pk_bf16_f32 v165, v128, v129
	ds_read_b64_tr_b16 v[114:115], v253 offset:1024
	ds_read_b64_tr_b16 v[116:117], v253 offset:1536
	s_waitcnt lgkmcnt(4)
	v_mfma_f32_32x32x16_bf16 v[66:81], v[186:189], v[142:145], v[66:81]
	v_exp_f32_e32 v98, v98
	v_exp_f32_e32 v99, v99
	v_exp_f32_e32 v100, v100
	v_exp_f32_e32 v101, v101
	s_waitcnt lgkmcnt(2)
	v_mfma_f32_32x32x16_bf16 v[2:17], v[214:217], v[130:133], v[2:17]
	ds_read_b64_tr_b16 v[118:119], v253 offset:2048
	ds_read_b64_tr_b16 v[120:121], v253 offset:2560
	v_add_f32_e32 v212, v98, v99
	v_add_f32_e32 v210, v212, v210
	v_add_f32_e32 v213, v101, v100
	v_add_f32_e32 v211, v213, v211
	v_cvt_pk_bf16_f32 v166, v98, v99
	v_cvt_pk_bf16_f32 v167, v100, v101
	s_waitcnt lgkmcnt(2)
	v_mfma_f32_32x32x16_bf16 v[2:17], v[114:117], v[134:137], v[2:17]
	ds_read_b64_tr_b16 v[214:215], v253 offset:3072
	ds_read_b64_tr_b16 v[216:217], v253 offset:3584
	s_waitcnt lgkmcnt(2)
	v_mfma_f32_32x32x16_bf16 v[2:17], v[118:121], v[138:141], v[2:17]
	ds_read_b64_tr_b16 v[114:115], v253 offset:4096
	ds_read_b64_tr_b16 v[116:117], v253 offset:4608
	v_exp_f32_e32 v102, v102
	v_exp_f32_e32 v103, v103
	v_exp_f32_e32 v104, v104
	v_exp_f32_e32 v105, v105
	s_waitcnt lgkmcnt(2)
	v_mfma_f32_32x32x16_bf16 v[2:17], v[214:217], v[190:193], v[2:17]
	ds_read_b64_tr_b16 v[118:119], v253 offset:5120
	ds_read_b64_tr_b16 v[120:121], v253 offset:5632
	v_add_f32_e32 v212, v102, v103
	v_add_f32_e32 v210, v212, v210
	v_add_f32_e32 v213, v105, v104
	v_add_f32_e32 v211, v213, v211
	v_cvt_pk_bf16_f32 v168, v102, v103
	v_cvt_pk_bf16_f32 v169, v104, v105
	s_waitcnt lgkmcnt(2)
	v_mfma_f32_32x32x16_bf16 v[2:17], v[114:117], v[194:197], v[2:17]
	ds_read_b64_tr_b16 v[214:215], v253 offset:6144
	ds_read_b64_tr_b16 v[216:217], v253 offset:6656
	s_waitcnt lgkmcnt(2)
	v_mfma_f32_32x32x16_bf16 v[2:17], v[118:121], v[198:201], v[2:17]
	ds_read_b64_tr_b16 v[114:115], v253 offset:7168
	ds_read_b64_tr_b16 v[116:117], v253 offset:7680
	v_exp_f32_e32 v106, v106
	v_exp_f32_e32 v107, v107
	v_exp_f32_e32 v108, v108
	v_exp_f32_e32 v109, v109
	s_waitcnt lgkmcnt(2)
	v_mfma_f32_32x32x16_bf16 v[2:17], v[214:217], v[202:205], v[2:17]
	ds_read_b64_tr_b16 v[118:119], v253 offset:8192
	ds_read_b64_tr_b16 v[120:121], v253 offset:8704
	v_add_f32_e32 v212, v106, v107
	v_add_f32_e32 v210, v212, v210
	v_add_f32_e32 v213, v109, v108
	v_add_f32_e32 v211, v213, v211
	v_cvt_pk_bf16_f32 v170, v106, v107
	v_cvt_pk_bf16_f32 v171, v108, v109
	s_waitcnt lgkmcnt(2)
	v_mfma_f32_32x32x16_bf16 v[2:17], v[114:117], v[206:209], v[2:17]
	ds_read_b64_tr_b16 v[214:215], v253 offset:9216
	ds_read_b64_tr_b16 v[216:217], v253 offset:9728
	v_exp_f32_e32 v110, v110
	v_exp_f32_e32 v111, v111
	v_exp_f32_e32 v112, v112
	v_exp_f32_e32 v113, v113
	s_waitcnt lgkmcnt(2)
	v_mfma_f32_32x32x16_bf16 v[50:65], v[118:121], v[130:133], v[50:65]
	ds_read_b64_tr_b16 v[114:115], v253 offset:10240
	ds_read_b64_tr_b16 v[116:117], v253 offset:10752
	s_waitcnt lgkmcnt(2)
	v_mfma_f32_32x32x16_bf16 v[50:65], v[214:217], v[134:137], v[50:65]
	ds_read_b64_tr_b16 v[118:119], v253 offset:11264
	ds_read_b64_tr_b16 v[120:121], v253 offset:11776
	v_add_f32_e32 v212, v110, v111
	v_add_f32_e32 v210, v212, v210
	v_add_f32_e32 v213, v113, v112
	v_add_f32_e32 v211, v213, v211
	v_cvt_pk_bf16_f32 v172, v110, v111
	v_cvt_pk_bf16_f32 v173, v112, v113
	s_waitcnt lgkmcnt(2)
	v_mfma_f32_32x32x16_bf16 v[50:65], v[114:117], v[138:141], v[50:65]
	ds_read_b64_tr_b16 v[214:215], v253 offset:12288
	ds_read_b64_tr_b16 v[216:217], v253 offset:12800
	v_exp_f32_e32 v82, v82
	v_exp_f32_e32 v83, v83
	v_exp_f32_e32 v84, v84
	v_exp_f32_e32 v85, v85
	s_waitcnt lgkmcnt(2)
	v_mfma_f32_32x32x16_bf16 v[50:65], v[118:121], v[190:193], v[50:65]
	ds_read_b64_tr_b16 v[114:115], v253 offset:13312
	ds_read_b64_tr_b16 v[116:117], v253 offset:13824
	s_waitcnt lgkmcnt(2)
	v_mfma_f32_32x32x16_bf16 v[50:65], v[214:217], v[194:197], v[50:65]
	ds_read_b64_tr_b16 v[118:119], v253 offset:14336
	ds_read_b64_tr_b16 v[120:121], v253 offset:14848
	v_add_f32_e32 v212, v82, v83
	v_add_f32_e32 v210, v212, v210
	v_add_f32_e32 v213, v85, v84
	v_add_f32_e32 v211, v213, v211
	v_cvt_pk_bf16_f32 v174, v82, v83
	v_cvt_pk_bf16_f32 v175, v84, v85
	s_waitcnt lgkmcnt(2)
	v_mfma_f32_32x32x16_bf16 v[50:65], v[114:117], v[198:201], v[50:65]
	ds_read_b64_tr_b16 v[214:215], v253 offset:15360
	ds_read_b64_tr_b16 v[216:217], v253 offset:15872
	v_exp_f32_e32 v86, v86
	v_exp_f32_e32 v87, v87
	v_exp_f32_e32 v88, v88
	v_exp_f32_e32 v89, v89
	s_waitcnt lgkmcnt(2)
; #define D8_FULL(WC_, WN_, t_, MASK_) do { const int tt = (t_); D8_HEAD(tt) D8_QKP(tt + 1, MASK_) D8_PVX(tt, WC_, true, WN_) } while (0)
; #define D8_LAST(WC_, t_) do { const int tt = (t_); D8_HEAD(tt) D8_PVX(tt, WC_, false, WC_) } while (0)
; __device__ __forceinline__ void df_unit_p128(ATT_LAS unsigned char* lds, const bf16_t* Q, const bf16_t* __restrict__ K, const bf16_t* __restrict__ V, bf16_t* O, int b, int h, int qb,
;                                              float lam, float post, const float* __restrict__ sub_g, const int wv) {
;     ...
;     for (; T + 2 <= qb - 1; T += 2) { D8_FULL(wa, wb, T, false); D8_FULL(wb, wa, T + 1, false); }
;     if (T < qb - 1) { D8_FULL(wa, wb, T, false); D8_FULL(wb, wa, T + 1, true); D8_LAST(wa, qb); }
	v_mfma_f32_32x32x16_bf16 v[50:65], v[118:121], v[202:205], v[50:65]
	ds_read_b64_tr_b16 v[114:115], v253 offset:16384
	ds_read_b64_tr_b16 v[116:117], v253 offset:16896
	v_add_f32_e32 v212, v86, v87
	v_add_f32_e32 v210, v212, v210
	v_add_f32_e32 v213, v89, v88
	v_add_f32_e32 v211, v213, v211
	v_cvt_pk_bf16_f32 v176, v86, v87
	v_cvt_pk_bf16_f32 v177, v88, v89
	s_waitcnt lgkmcnt(2)
	v_mfma_f32_32x32x16_bf16 v[50:65], v[214:217], v[206:209], v[50:65]
	ds_read_b64_tr_b16 v[118:119], v253 offset:17408
	ds_read_b64_tr_b16 v[120:121], v253 offset:17920
	s_waitcnt lgkmcnt(2)
	v_mfma_f32_32x32x16_bf16 v[34:49], v[114:117], v[130:133], v[34:49]
	ds_read_b64_tr_b16 v[214:215], v253 offset:18432
	ds_read_b64_tr_b16 v[216:217], v253 offset:18944
	v_exp_f32_e32 v90, v90
	v_exp_f32_e32 v91, v91
	v_exp_f32_e32 v92, v92
	v_exp_f32_e32 v93, v93
	s_waitcnt lgkmcnt(2)
	v_mfma_f32_32x32x16_bf16 v[34:49], v[118:121], v[134:137], v[34:49]
	ds_read_b64_tr_b16 v[114:115], v253 offset:19456
	ds_read_b64_tr_b16 v[116:117], v253 offset:19968
	v_add_f32_e32 v212, v90, v91
	v_add_f32_e32 v210, v212, v210
	v_add_f32_e32 v213, v93, v92
	v_add_f32_e32 v211, v213, v211
	v_cvt_pk_bf16_f32 v178, v90, v91
	v_cvt_pk_bf16_f32 v179, v92, v93
	s_waitcnt lgkmcnt(2)
	v_mfma_f32_32x32x16_bf16 v[34:49], v[214:217], v[138:141], v[34:49]
	ds_read_b64_tr_b16 v[118:119], v253 offset:20480
	ds_read_b64_tr_b16 v[120:121], v253 offset:20992
	v_exp_f32_e32 v94, v94
	v_exp_f32_e32 v95, v95
	v_exp_f32_e32 v96, v96
	v_exp_f32_e32 v97, v97
	s_waitcnt lgkmcnt(2)
	v_mfma_f32_32x32x16_bf16 v[34:49], v[114:117], v[190:193], v[34:49]
	ds_read_b64_tr_b16 v[214:215], v253 offset:21504
	ds_read_b64_tr_b16 v[216:217], v253 offset:22016
	s_waitcnt lgkmcnt(2)
	v_mfma_f32_32x32x16_bf16 v[34:49], v[118:121], v[194:197], v[34:49]
	ds_read_b64_tr_b16 v[114:115], v253 offset:22528
	ds_read_b64_tr_b16 v[116:117], v253 offset:23040
	v_add_f32_e32 v212, v94, v95
	v_add_f32_e32 v210, v212, v210
	v_add_f32_e32 v213, v97, v96
	v_add_f32_e32 v211, v213, v211
	v_cvt_pk_bf16_f32 v180, v94, v95
	v_cvt_pk_bf16_f32 v181, v96, v97
	s_waitcnt lgkmcnt(2)
	v_mfma_f32_32x32x16_bf16 v[34:49], v[214:217], v[198:201], v[34:49]
	ds_read_b64_tr_b16 v[118:119], v253 offset:23552
	ds_read_b64_tr_b16 v[120:121], v253 offset:24064
	v_exp_f32_e32 v66, v66
	v_exp_f32_e32 v67, v67
	v_exp_f32_e32 v68, v68
	v_exp_f32_e32 v69, v69
	s_waitcnt lgkmcnt(2)
	v_mfma_f32_32x32x16_bf16 v[34:49], v[114:117], v[202:205], v[34:49]
	ds_read_b64_tr_b16 v[214:215], v253 offset:24576
	ds_read_b64_tr_b16 v[216:217], v253 offset:25088
	s_waitcnt lgkmcnt(2)
	v_mfma_f32_32x32x16_bf16 v[34:49], v[118:121], v[206:209], v[34:49]
	ds_read_b64_tr_b16 v[114:115], v253 offset:25600
	ds_read_b64_tr_b16 v[116:117], v253 offset:26112
	v_add_f32_e32 v212, v66, v67
	v_add_f32_e32 v210, v212, v210
	v_add_f32_e32 v213, v69, v68
	v_add_f32_e32 v211, v213, v211
	v_cvt_pk_bf16_f32 v182, v66, v67
	v_cvt_pk_bf16_f32 v183, v68, v69
	s_waitcnt lgkmcnt(2)
	v_mfma_f32_32x32x16_bf16 v[18:33], v[214:217], v[130:133], v[18:33]
	ds_read_b64_tr_b16 v[118:119], v253 offset:26624
	ds_read_b64_tr_b16 v[120:121], v253 offset:27136
	v_exp_f32_e32 v70, v70
	v_exp_f32_e32 v71, v71
	v_exp_f32_e32 v72, v72
	v_exp_f32_e32 v73, v73
	s_waitcnt lgkmcnt(2)
	v_mfma_f32_32x32x16_bf16 v[18:33], v[114:117], v[134:137], v[18:33]
	ds_read_b64_tr_b16 v[214:215], v253 offset:27648
	ds_read_b64_tr_b16 v[216:217], v253 offset:28160
	v_add_f32_e32 v212, v70, v71
	v_add_f32_e32 v210, v212, v210
	v_add_f32_e32 v213, v73, v72
	v_add_f32_e32 v211, v213, v211
	v_cvt_pk_bf16_f32 v184, v70, v71
	v_cvt_pk_bf16_f32 v185, v72, v73
	s_waitcnt lgkmcnt(2)
	v_mfma_f32_32x32x16_bf16 v[18:33], v[118:121], v[138:141], v[18:33]
	ds_read_b64_tr_b16 v[114:115], v253 offset:28672
	ds_read_b64_tr_b16 v[116:117], v253 offset:29184
	s_waitcnt lgkmcnt(2)
	v_mfma_f32_32x32x16_bf16 v[18:33], v[214:217], v[190:193], v[18:33]
	ds_read_b64_tr_b16 v[118:119], v253 offset:29696
	ds_read_b64_tr_b16 v[120:121], v253 offset:30208
	v_exp_f32_e32 v74, v74
	v_exp_f32_e32 v75, v75
	v_exp_f32_e32 v76, v76
	v_exp_f32_e32 v77, v77
	s_waitcnt lgkmcnt(2)
	v_mfma_f32_32x32x16_bf16 v[18:33], v[114:117], v[194:197], v[18:33]
	ds_read_b64_tr_b16 v[214:215], v253 offset:30720
	ds_read_b64_tr_b16 v[216:217], v253 offset:31232
	v_add_f32_e32 v212, v74, v75
	v_add_f32_e32 v210, v212, v210
	v_add_f32_e32 v213, v77, v76
	v_add_f32_e32 v211, v213, v211
	v_cvt_pk_bf16_f32 v186, v74, v75
	v_cvt_pk_bf16_f32 v187, v76, v77
	s_waitcnt lgkmcnt(2)
	v_mfma_f32_32x32x16_bf16 v[18:33], v[118:121], v[198:201], v[18:33]
	ds_read_b64_tr_b16 v[114:115], v253 offset:31744
	ds_read_b64_tr_b16 v[116:117], v253 offset:32256
	s_waitcnt lgkmcnt(2)
	v_mfma_f32_32x32x16_bf16 v[18:33], v[214:217], v[202:205], v[18:33]
	v_exp_f32_e32 v78, v78
	v_exp_f32_e32 v79, v79
	v_exp_f32_e32 v80, v80
	v_exp_f32_e32 v81, v81
	s_waitcnt lgkmcnt(0)
	v_mfma_f32_32x32x16_bf16 v[18:33], v[114:117], v[206:209], v[18:33]
	v_add_f32_e32 v212, v78, v79
	v_add_f32_e32 v210, v212, v210
	v_add_f32_e32 v213, v81, v80
	v_add_f32_e32 v211, v213, v211
	v_cvt_pk_bf16_f32 v188, v78, v79
	v_cvt_pk_bf16_f32 v189, v80, v81
	s_add_i32 s39, s39, 2
	s_add_u32 s16, s16, 0x80000
	v_add_f32_e32 v212, v247, v241
	v_add_f32_e32 v213, v211, v210
	s_addc_u32 s17, s17, 0
	s_add_i32 s18, s18, 4
	s_cmp_lt_u32 s18, s25
	v_add_f32_e32 v247, v212, v213
	s_cbranch_scc1 .LBB0_220
	s_nop 0
	s_mov_b32 s19, s55
	s_lshl_b64 s[16:17], s[18:19], 18
	v_mov_b64_e32 v[226:227], 0x600
	v_mov_b64_e32 v[228:229], 0x5ff
	v_mov_b64_e32 v[232:233], 0x200
	v_mov_b64_e32 v[234:235], 0x1ff
	s_add_i32 s18, s23, 30
	s_cmp_ge_i32 s39, s18
	s_mov_b64 s[18:19], -1
	s_cbranch_scc0 .LBB0_229
	s_branch .LBB0_223

; __global__ void __launch_bounds__(NWAVES * 64) fwd_mega(Params p) {
;     extern __shared__ __attribute__((aligned(16))) unsigned char lds_raw[];
	.amdhsa_kernel _Z8fwd_mega6Params
		.amdhsa_group_segment_fixed_size 0
		.amdhsa_private_segment_fixed_size 0
		.amdhsa_kernarg_size 448
		.amdhsa_user_sgpr_count 2
		.amdhsa_user_sgpr_dispatch_ptr 0
		.amdhsa_user_sgpr_queue_ptr 0
		.amdhsa_user_sgpr_kernarg_segment_ptr 1
		.amdhsa_user_sgpr_dispatch_id 0
		.amdhsa_user_sgpr_kernarg_preload_length 0
		.amdhsa_user_sgpr_kernarg_preload_offset 0
		.amdhsa_user_sgpr_private_segment_size 0
		.amdhsa_uses_dynamic_stack 0
		.amdhsa_enable_private_segment 0
		.amdhsa_system_sgpr_workgroup_id_x 1
		.amdhsa_system_sgpr_workgroup_id_y 0
		.amdhsa_system_sgpr_workgroup_id_z 0
		.amdhsa_system_sgpr_workgroup_info 0
		.amdhsa_system_vgpr_workitem_id 2
		.amdhsa_next_free_vgpr 256
		.amdhsa_next_free_sgpr 100
		.amdhsa_accum_offset 256
		.amdhsa_reserve_vcc 1
		.amdhsa_float_round_mode_32 0
		.amdhsa_float_round_mode_16_64 0
		.amdhsa_float_denorm_mode_32 3
		.amdhsa_float_denorm_mode_16_64 3
		.amdhsa_dx10_clamp 1
		.amdhsa_ieee_mode 1
		.amdhsa_fp16_overflow 0
		.amdhsa_tg_split 0
		.amdhsa_exception_fp_ieee_invalid_op 0
		.amdhsa_exception_fp_denorm_src 0
		.amdhsa_exception_fp_ieee_div_zero 0
		.amdhsa_exception_fp_ieee_overflow 0
		.amdhsa_exception_fp_ieee_underflow 0
		.amdhsa_exception_fp_ieee_inexact 0
		.amdhsa_exception_int_div_zero 0
	.end_amdhsa_kernel

; __global__ void __launch_bounds__(NWAVES * 64) fwd_mega(Params p) {
;     extern __shared__ __attribute__((aligned(16))) unsigned char lds_raw[];
amdhsa.kernels:
  - .agpr_count:     0
    .args:
      - .offset:         0
        .size:           192
        .value_kind:     by_value
      - .offset:         192
        .size:           4
        .value_kind:     hidden_block_count_x
      - .offset:         196
        .size:           4
        .value_kind:     hidden_block_count_y
      - .offset:         200
        .size:           4
        .value_kind:     hidden_block_count_z
      - .offset:         204
        .size:           2
        .value_kind:     hidden_group_size_x
      - .offset:         206
        .size:           2
        .value_kind:     hidden_group_size_y
      - .offset:         208
        .size:           2
        .value_kind:     hidden_group_size_z
      - .offset:         210
        .size:           2
        .value_kind:     hidden_remainder_x
      - .offset:         212
        .size:           2
        .value_kind:     hidden_remainder_y
      - .offset:         214
        .size:           2
        .value_kind:     hidden_remainder_z
      - .offset:         232
        .size:           8
        .value_kind:     hidden_global_offset_x
      - .offset:         240
        .size:           8
        .value_kind:     hidden_global_offset_y
      - .offset:         248
        .size:           8
        .value_kind:     hidden_global_offset_z
      - .offset:         256
        .size:           2
        .value_kind:     hidden_grid_dims
      - .offset:         280
        .size:           8
        .value_kind:     hidden_multigrid_sync_arg
      - .offset:         312
        .size:           4
        .value_kind:     hidden_dynamic_lds_size
    .group_segment_fixed_size: 0
    .kernarg_segment_align: 8
    .kernarg_segment_size: 448
    .language:       OpenCL C
    .language_version:
      - 2
      - 0
    .max_flat_workgroup_size: 512
    .name:           _Z8fwd_mega6Params
    .private_segment_fixed_size: 0
    .sgpr_count:     106
    .sgpr_spill_count: 128
    .symbol:         _Z8fwd_mega6Params.kd
    .uniform_work_group_size: 1
    .uses_dynamic_stack: false
    .vgpr_count:     256
    .vgpr_spill_count: 0
    .wavefront_size: 64
